# prologue weight transposes: 8 gain loads hoisted behind the data loads (one wait instead of 4 dependent stages), on top of v2
# speedup vs baseline: 1.0090x; 1.0005x over previous
.LBB0_85:
	s_abs_i32 s5, s78
	s_mul_hi_u32 s6, s5, s74
	s_mul_i32 s36, s6, s69
	s_sub_i32 s5, s5, s36
	s_ashr_i32 s4, s78, 31
	s_add_i32 s36, s6, 1
	s_sub_i32 s37, s5, s69
	s_cmp_ge_u32 s5, s69
	s_cselect_b32 s6, s36, s6
	s_cselect_b32 s5, s37, s5
	s_add_i32 s36, s6, 1
	s_cmp_ge_u32 s5, s69
	s_cselect_b32 s5, s36, s6
	s_xor_b32 s5, s5, s4
	s_sub_i32 s80, s5, s4
	s_lshl_b32 s36, s80, 6
	s_mul_i32 s81, s73, s80
	v_or_b32_e32 v44, s36, v40
	s_add_i32 s79, s75, s81
	v_ashrrev_i32_e32 v45, 31, v44
	v_or_b32_e32 v4, 8, v44
	s_add_i32 s4, s79, 0x200
	v_mul_lo_u32 v6, v45, s68
	v_mad_u64_u32 v[2:3], s[38:39], v44, s68, 0
	v_mad_u64_u32 v[4:5], s[38:39], v4, s68, 0
	s_ashr_i32 s5, s4, 31
	v_add_u32_e32 v3, v3, v6
	v_add_u32_e32 v5, v5, v6
	v_lshl_add_u64 v[2:3], v[2:3], 2, s[8:9]
	s_lshl_b64 s[4:5], s[4:5], 2
	v_lshl_add_u64 v[4:5], v[4:5], 2, s[8:9]
	v_lshl_add_u64 v[2:3], v[2:3], 0, s[4:5]
	v_lshl_add_u64 v[4:5], v[4:5], 0, s[4:5]
	v_lshl_add_u64 v[2:3], v[2:3], 0, v[42:43]
	v_lshl_add_u64 v[4:5], v[4:5], 0, v[42:43]
	global_load_dwordx4 v[30:33], v[2:3], off
	global_load_dwordx4 v[26:29], v[4:5], off
	v_or_b32_e32 v2, 16, v44
	v_or_b32_e32 v4, 24, v44
	v_mad_u64_u32 v[2:3], s[38:39], v2, s68, 0
	v_mad_u64_u32 v[4:5], s[38:39], v4, s68, 0
	v_add_u32_e32 v3, v3, v6
	v_add_u32_e32 v5, v5, v6
	v_lshl_add_u64 v[2:3], v[2:3], 2, s[8:9]
	v_lshl_add_u64 v[4:5], v[4:5], 2, s[8:9]
	v_lshl_add_u64 v[2:3], v[2:3], 0, s[4:5]
	v_lshl_add_u64 v[4:5], v[4:5], 0, s[4:5]
	v_lshl_add_u64 v[2:3], v[2:3], 0, v[42:43]
	v_lshl_add_u64 v[4:5], v[4:5], 0, v[42:43]
	global_load_dwordx4 v[22:25], v[2:3], off
	global_load_dwordx4 v[18:21], v[4:5], off
	v_or_b32_e32 v2, 32, v44
	v_or_b32_e32 v4, 40, v44
	v_mad_u64_u32 v[2:3], s[38:39], v2, s68, 0
	v_mad_u64_u32 v[4:5], s[38:39], v4, s68, 0
	v_add_u32_e32 v3, v3, v6
	v_add_u32_e32 v5, v5, v6
	v_lshl_add_u64 v[2:3], v[2:3], 2, s[8:9]
	v_lshl_add_u64 v[4:5], v[4:5], 2, s[8:9]
	v_lshl_add_u64 v[2:3], v[2:3], 0, s[4:5]
	v_lshl_add_u64 v[4:5], v[4:5], 0, s[4:5]
	v_lshl_add_u64 v[2:3], v[2:3], 0, v[42:43]
	v_lshl_add_u64 v[4:5], v[4:5], 0, v[42:43]
	global_load_dwordx4 v[14:17], v[2:3], off
	global_load_dwordx4 v[10:13], v[4:5], off
	v_or_b32_e32 v2, 48, v44
	v_or_b32_e32 v4, 56, v44
	v_mad_u64_u32 v[2:3], s[38:39], v2, s68, 0
	v_mad_u64_u32 v[4:5], s[38:39], v4, s68, 0
	v_add_u32_e32 v3, v3, v6
	v_add_u32_e32 v5, v5, v6
	v_lshl_add_u64 v[2:3], v[2:3], 2, s[8:9]
	v_lshl_add_u64 v[4:5], v[4:5], 2, s[8:9]
	v_lshl_add_u64 v[2:3], v[2:3], 0, s[4:5]
	v_lshl_add_u64 v[4:5], v[4:5], 0, s[4:5]
	v_lshl_add_u64 v[2:3], v[2:3], 0, v[42:43]
	v_lshl_add_u64 v[4:5], v[4:5], 0, v[42:43]
	global_load_dwordx4 v[6:9], v[2:3], off
	s_nop 0
	global_load_dwordx4 v[2:5], v[4:5], off
	s_ashr_i32 s37, s36, 31
	v_mov_b32_e32 v62, 1.0
	v_mov_b32_e32 v64, 1.0
	v_mov_b32_e32 v66, 1.0
	v_mov_b32_e32 v68, 1.0
	v_mov_b32_e32 v70, 1.0
	v_mov_b32_e32 v72, 1.0
	v_mov_b32_e32 v74, 1.0
	v_mov_b32_e32 v76, 1.0
	s_andn2_b64 vcc, exec, s[34:35]
	s_cbranch_vccnz .Ltr_nogain
	v_lshl_add_u64 v[78:79], s[36:37], 0, v[40:41]
	v_lshl_add_u64 v[78:79], v[78:79], 2, s[10:11]
	global_load_dword v62, v[78:79], off
	global_load_dword v64, v[78:79], off offset:32
	global_load_dword v66, v[78:79], off offset:64
	global_load_dword v68, v[78:79], off offset:96
	global_load_dword v70, v[78:79], off offset:128
	global_load_dword v72, v[78:79], off offset:160
	global_load_dword v74, v[78:79], off offset:192
	global_load_dword v76, v[78:79], off offset:224
.Ltr_nogain:
	s_waitcnt vmcnt(0)
	v_pk_mul_f32 v[30:31], v[30:31], v[62:63] op_sel_hi:[1,0]
	v_pk_mul_f32 v[32:33], v[32:33], v[62:63] op_sel_hi:[1,0]
	ds_write2_b32 v57, v30, v31 offset1:1
	ds_write2_b32 v57, v32, v33 offset0:2 offset1:3
	v_pk_mul_f32 v[26:27], v[26:27], v[64:65] op_sel_hi:[1,0]
	v_pk_mul_f32 v[28:29], v[28:29], v[64:65] op_sel_hi:[1,0]
	v_add_u32_e32 v80, 0x420, v57
	ds_write2_b32 v80, v26, v27 offset1:1
	ds_write2_b32 v80, v28, v29 offset0:2 offset1:3
	v_pk_mul_f32 v[22:23], v[22:23], v[66:67] op_sel_hi:[1,0]
	v_pk_mul_f32 v[24:25], v[24:25], v[66:67] op_sel_hi:[1,0]
	v_add_u32_e32 v82, 0x840, v57
	ds_write2_b32 v82, v22, v23 offset1:1
	ds_write2_b32 v82, v24, v25 offset0:2 offset1:3
	v_pk_mul_f32 v[18:19], v[18:19], v[68:69] op_sel_hi:[1,0]
	v_pk_mul_f32 v[20:21], v[20:21], v[68:69] op_sel_hi:[1,0]
	v_add_u32_e32 v80, 0xc60, v57
	ds_write2_b32 v80, v18, v19 offset1:1
	ds_write2_b32 v80, v20, v21 offset0:2 offset1:3
	v_pk_mul_f32 v[14:15], v[14:15], v[70:71] op_sel_hi:[1,0]
	v_pk_mul_f32 v[16:17], v[16:17], v[70:71] op_sel_hi:[1,0]
	v_add_u32_e32 v82, 0x1080, v57
	ds_write2_b32 v82, v14, v15 offset1:1
	ds_write2_b32 v82, v16, v17 offset0:2 offset1:3
	v_pk_mul_f32 v[10:11], v[10:11], v[72:73] op_sel_hi:[1,0]
	v_pk_mul_f32 v[12:13], v[12:13], v[72:73] op_sel_hi:[1,0]
	v_add_u32_e32 v80, 0x14a0, v57
	ds_write2_b32 v80, v10, v11 offset1:1
	ds_write2_b32 v80, v12, v13 offset0:2 offset1:3
	v_pk_mul_f32 v[6:7], v[6:7], v[74:75] op_sel_hi:[1,0]
	v_pk_mul_f32 v[8:9], v[8:9], v[74:75] op_sel_hi:[1,0]
	v_add_u32_e32 v82, 0x18c0, v57
	ds_write2_b32 v82, v6, v7 offset1:1
	ds_write2_b32 v82, v8, v9 offset0:2 offset1:3
	v_pk_mul_f32 v[2:3], v[2:3], v[76:77] op_sel_hi:[1,0]
	v_pk_mul_f32 v[4:5], v[4:5], v[76:77] op_sel_hi:[1,0]
	v_add_u32_e32 v80, 0x1ce0, v57
	ds_write2_b32 v80, v2, v3 offset1:1
	ds_write2_b32 v80, v4, v5 offset0:2 offset1:3
	s_waitcnt lgkmcnt(0)
	ds_read2_b32 v[2:3], v51 offset1:33
	s_waitcnt lgkmcnt(0)
	v_cvt_pk_bf16_f32 v2, v2, v3
	ds_read2_b32 v[4:5], v51 offset0:66 offset1:99
	s_waitcnt lgkmcnt(0)
	v_cvt_pk_bf16_f32 v3, v4, v5
	ds_read2_b32 v[4:5], v51 offset0:132 offset1:165
	s_waitcnt lgkmcnt(0)
	v_cvt_pk_bf16_f32 v4, v4, v5
	ds_read2_b32 v[6:7], v51 offset0:198 offset1:231
	s_mul_i32 s4, s80, s69
	s_waitcnt lgkmcnt(0)
	v_cvt_pk_bf16_f32 v5, v6, v7
	s_sub_i32 s4, s78, s4
	v_add_u32_e32 v7, s75, v40
	s_lshl_b32 s82, s4, 5
	v_add_u32_e32 v6, s81, v7
	v_or_b32_e32 v8, s82, v40
	v_add_u32_e32 v9, 0x200, v6
	s_cmp_lt_i32 s67, 3
	s_mov_b64 s[38:39], -1
	s_cbranch_scc1 .LBB0_106
	s_cmp_lt_i32 s67, 4
	s_mov_b64 s[4:5], -1
	s_cbranch_scc1 .LBB0_104
	s_cmp_eq_u32 s67, 4
	v_mov_b32_e32 v10, v8
	s_cbranch_scc0 .LBB0_103
	v_cmp_gt_i32_e32 vcc, s59, v9
	v_and_b32_e32 v11, 0x67, v9
	s_and_saveexec_b64 s[4:5], vcc
	s_xor_b64 s[4:5], exec, s[4:5]
	s_mul_i32 s6, s72, s80
	s_add_i32 s6, s76, s6
	s_and_b32 s6, s6, 0xffffff00
	s_addk_i32 s6, 0xf800
	v_or_b32_e32 v10, s6, v11
	v_cmp_lt_i32_e32 vcc, s60, v9
	s_nop 1
	v_cndmask_b32_e32 v10, v9, v10, vcc
	s_andn2_saveexec_b64 s[4:5], s[4:5]
	s_mul_i32 s6, s72, s80
	s_add_i32 s6, s76, s6
	s_and_b32 s6, s6, 0xffffff00
	s_addk_i32 s6, 0xe880
	v_or_b32_e32 v10, s6, v11
	s_or_b64 exec, exec, s[4:5]

.LBB0_194:
	s_andn2_b64 vcc, exec, s[4:5]
	s_cbranch_vccnz .LBB0_83
	s_cmp_eq_u32 s67, 1
	s_cbranch_scc0 .LBB0_82
	v_cmp_lt_i32_e32 vcc, s65, v9
	s_and_saveexec_b64 s[4:5], vcc
	s_xor_b64 s[4:5], exec, s[4:5]
	s_mul_i32 s6, s72, s80
	s_add_i32 s6, s6, s76
	v_add3_u32 v6, s6, v52, 48
	s_lshr_b32 s6, s79, 5
	v_and_b32_e32 v6, 62, v6
	s_addk_i32 s6, 0x400
	v_add_u32_e32 v8, s6, v6
	s_andn2_saveexec_b64 s[4:5], s[4:5]
	s_cbranch_execz .LBB0_81
	v_add_u32_e32 v8, 0x418, v6
	s_branch .LBB0_81

